# v12 + FFN-up (EpiSwiglu) epilogues: 8 per-row-group serialized ssq load/vmcnt(0)/bpermute/rsqrt chains batched at epilogue head (8 loads in flight, no vmcnt stall behind stores)
# speedup vs baseline: 1.0352x; 1.0025x over previous
; __device__ __forceinline__ float row_ssq(const float* part, int pitch, int n4, int row, int fq) {
;     f32x4 v = (f32x4){0.f, 0.f, 0.f, 0.f};
;     if (fq < n4) v = *(const f32x4*)(part + (size_t)row * pitch + 4 * fq);
;     float s = (v[0] + v[1]) + (v[2] + v[3]);
;     s += __shfl_xor(s, 16); s += __shfl_xor(s, 32);
;     return s;
; }
;     __device__ __forceinline__ void operator()(const f32x4 (&acc)[2][2][4][2], const Unit& u, int wr, int wc, int fr, int fq) const {
;         const int row0 = u.pm * BM + wr * 64 + fr, col0 = u.pn * 128 + wc * 32 + 8 * fq;
; #pragma unroll
;         for (int ai = 0; ai < 2; ++ai)
; #pragma unroll
;             for (int m = 0; m < 4; ++m) {
;                 const int row = row0 + ai * HALF + m * 16;
;                 const float rs = rsqrtf(row_ssq(ssq, 16, 4, row, fq) * (1.f / 1024.f) + EPS);
.LBB0_168:
	v_and_b32_e32 v145, 64, v241
	v_xor_b32_e32 v143, 16, v241
	v_add_u32_e32 v145, 64, v145
	v_cmp_lt_i32_e32 vcc, v143, v145
	v_lshl_add_u32 v144, s44, 8, v146
	v_lshl_or_b32 v142, s4, 7, v148
	v_cndmask_b32_e32 v143, v241, v143, vcc
	v_lshlrev_b32_e32 v150, 2, v143
	v_xor_b32_e32 v143, 32, v241
	v_cmp_lt_i32_e32 vcc, v143, v145
	v_ashrrev_i32_e32 v145, 31, v144
	v_lshlrev_b64 v[166:167], 6, v[144:145]
	v_lshl_add_u64 v[166:167], v[136:137], 0, v[166:167]
	global_load_dwordx4 v[168:171], v[166:167], off
	global_load_dwordx4 v[172:175], v[166:167], off offset:1024
	global_load_dwordx4 v[176:179], v[166:167], off offset:2048
	global_load_dwordx4 v[180:183], v[166:167], off offset:3072
	v_cndmask_b32_e32 v143, v241, v143, vcc
	v_add_co_u32_e32 v166, vcc, 0x2000, v166
	v_lshlrev_b32_e32 v151, 2, v143
	v_addc_co_u32_e32 v167, vcc, 0, v167, vcc
	global_load_dwordx4 v[184:187], v[166:167], off
	global_load_dwordx4 v[188:191], v[166:167], off offset:1024
	global_load_dwordx4 v[192:195], v[166:167], off offset:2048
	global_load_dwordx4 v[196:199], v[166:167], off offset:3072
	v_ashrrev_i32_e32 v143, 31, v142
	v_lshl_add_u64 v[142:143], v[142:143], 1, s[96:97]
	s_movk_i32 s4, 0x1600
	s_mov_b64 s[24:25], -1
	s_waitcnt vmcnt(7)
	v_add_f32_e32 v168, v169, v168
	v_add_f32_e32 v170, v170, v171
	v_add_f32_e32 v168, v168, v170
	ds_bpermute_b32 v169, v150, v168
	s_waitcnt vmcnt(6)
	v_add_f32_e32 v172, v173, v172
	v_add_f32_e32 v174, v174, v175
	v_add_f32_e32 v172, v172, v174
	ds_bpermute_b32 v173, v150, v172
	s_waitcnt vmcnt(5)
	v_add_f32_e32 v176, v177, v176
	v_add_f32_e32 v178, v178, v179
	v_add_f32_e32 v176, v176, v178
	ds_bpermute_b32 v177, v150, v176
	s_waitcnt vmcnt(4)
	v_add_f32_e32 v180, v181, v180
	v_add_f32_e32 v182, v182, v183
	v_add_f32_e32 v180, v180, v182
	ds_bpermute_b32 v181, v150, v180
	s_waitcnt vmcnt(3)
	v_add_f32_e32 v184, v185, v184
	v_add_f32_e32 v186, v186, v187
	v_add_f32_e32 v184, v184, v186
	ds_bpermute_b32 v185, v150, v184
	s_waitcnt vmcnt(2)
	v_add_f32_e32 v188, v189, v188
	v_add_f32_e32 v190, v190, v191
	v_add_f32_e32 v188, v188, v190
	ds_bpermute_b32 v189, v150, v188
	s_waitcnt vmcnt(1)
	v_add_f32_e32 v192, v193, v192
	v_add_f32_e32 v194, v194, v195
	v_add_f32_e32 v192, v192, v194
	ds_bpermute_b32 v193, v150, v192
	s_waitcnt vmcnt(0)
	v_add_f32_e32 v196, v197, v196
	v_add_f32_e32 v198, v198, v199
	v_add_f32_e32 v196, v196, v198
	ds_bpermute_b32 v197, v150, v196
	s_waitcnt lgkmcnt(7)
	v_add_f32_e32 v168, v168, v169
	ds_bpermute_b32 v169, v151, v168
	s_waitcnt lgkmcnt(7)
	v_add_f32_e32 v172, v172, v173
	ds_bpermute_b32 v173, v151, v172
	s_waitcnt lgkmcnt(7)
	v_add_f32_e32 v176, v176, v177
	ds_bpermute_b32 v177, v151, v176
	s_waitcnt lgkmcnt(7)
	v_add_f32_e32 v180, v180, v181
	ds_bpermute_b32 v181, v151, v180
	s_waitcnt lgkmcnt(7)
	v_add_f32_e32 v184, v184, v185
	ds_bpermute_b32 v185, v151, v184
	s_waitcnt lgkmcnt(7)
	v_add_f32_e32 v188, v188, v189
	ds_bpermute_b32 v189, v151, v188
	s_waitcnt lgkmcnt(7)
	v_add_f32_e32 v192, v192, v193
	ds_bpermute_b32 v193, v151, v192
	s_waitcnt lgkmcnt(7)
	v_add_f32_e32 v196, v196, v197
	ds_bpermute_b32 v197, v151, v196
	s_waitcnt lgkmcnt(7)
	v_add_f32_e32 v168, v168, v169
	v_fmamk_f32 v168, v168, 0x3a800000, v239
	s_waitcnt lgkmcnt(6)
	v_add_f32_e32 v172, v172, v173
	v_fmamk_f32 v172, v172, 0x3a800000, v239
	s_waitcnt lgkmcnt(5)
	v_add_f32_e32 v176, v176, v177
	v_fmamk_f32 v176, v176, 0x3a800000, v239
	s_waitcnt lgkmcnt(4)
	v_add_f32_e32 v180, v180, v181
	v_fmamk_f32 v180, v180, 0x3a800000, v239
	s_waitcnt lgkmcnt(3)
	v_add_f32_e32 v184, v184, v185
	v_fmamk_f32 v184, v184, 0x3a800000, v239
	s_waitcnt lgkmcnt(2)
	v_add_f32_e32 v188, v188, v189
	v_fmamk_f32 v188, v188, 0x3a800000, v239
	s_waitcnt lgkmcnt(1)
	v_add_f32_e32 v192, v192, v193
	v_fmamk_f32 v192, v192, 0x3a800000, v239
	s_waitcnt lgkmcnt(0)
	v_add_f32_e32 v196, v196, v197
	v_fmamk_f32 v196, v196, 0x3a800000, v239
	v_cmp_gt_f32_e32 vcc, s55, v168
	v_mul_f32_e32 v169, 0x4b800000, v168
	s_nop 0
	v_cndmask_b32_e32 v168, v168, v169, vcc
	v_rsq_f32_e32 v168, v168
	s_nop 0
	v_mul_f32_e32 v169, 0x45800000, v168
	v_cndmask_b32_e32 v158, v168, v169, vcc
	v_cmp_gt_f32_e32 vcc, s55, v172
	v_mul_f32_e32 v173, 0x4b800000, v172
	s_nop 0
	v_cndmask_b32_e32 v172, v172, v173, vcc
	v_rsq_f32_e32 v172, v172
	s_nop 0
	v_mul_f32_e32 v173, 0x45800000, v172
	v_cndmask_b32_e32 v159, v172, v173, vcc
	v_cmp_gt_f32_e32 vcc, s55, v176
	v_mul_f32_e32 v177, 0x4b800000, v176
	s_nop 0
	v_cndmask_b32_e32 v176, v176, v177, vcc
	v_rsq_f32_e32 v176, v176
	s_nop 0
	v_mul_f32_e32 v177, 0x45800000, v176
	v_cndmask_b32_e32 v160, v176, v177, vcc
	v_cmp_gt_f32_e32 vcc, s55, v180
	v_mul_f32_e32 v181, 0x4b800000, v180
	s_nop 0
	v_cndmask_b32_e32 v180, v180, v181, vcc
	v_rsq_f32_e32 v180, v180
	s_nop 0
	v_mul_f32_e32 v181, 0x45800000, v180
	v_cndmask_b32_e32 v161, v180, v181, vcc
	v_cmp_gt_f32_e32 vcc, s55, v184
	v_mul_f32_e32 v185, 0x4b800000, v184
	s_nop 0
	v_cndmask_b32_e32 v184, v184, v185, vcc
	v_rsq_f32_e32 v184, v184
	s_nop 0
	v_mul_f32_e32 v185, 0x45800000, v184
	v_cndmask_b32_e32 v162, v184, v185, vcc
	v_cmp_gt_f32_e32 vcc, s55, v188
	v_mul_f32_e32 v189, 0x4b800000, v188
	s_nop 0
	v_cndmask_b32_e32 v188, v188, v189, vcc
	v_rsq_f32_e32 v188, v188
	s_nop 0
	v_mul_f32_e32 v189, 0x45800000, v188
	v_cndmask_b32_e32 v163, v188, v189, vcc
	v_cmp_gt_f32_e32 vcc, s55, v192
	v_mul_f32_e32 v193, 0x4b800000, v192
	s_nop 0
	v_cndmask_b32_e32 v192, v192, v193, vcc
	v_rsq_f32_e32 v192, v192
	s_nop 0
	v_mul_f32_e32 v193, 0x45800000, v192
	v_cndmask_b32_e32 v164, v192, v193, vcc
	v_cmp_gt_f32_e32 vcc, s55, v196
	v_mul_f32_e32 v197, 0x4b800000, v196
	s_nop 0
; __device__ __forceinline__ unsigned pk2(float lo, float hi) { f32x2_t v = {lo, hi}; bf16x2_t b = __builtin_convertvector(v, bf16x2_t); return __builtin_bit_cast(unsigned, b); }
; __device__ __forceinline__ float fast_sigmoid(float x) { return __builtin_amdgcn_rcpf(1.f + __expf(-x)); }
;     __device__ __forceinline__ void operator()(const f32x4 (&acc)[2][2][4][2], const Unit& u, int wr, int wc, int fr, int fq) const {
;         const int row0 = u.pm * BM + wr * 64 + fr, col0 = u.pn * 128 + wc * 32 + 8 * fq;
; #pragma unroll
;         for (int ai = 0; ai < 2; ++ai)
; #pragma unroll
;             for (int m = 0; m < 4; ++m) {
;                 const int row = row0 + ai * HALF + m * 16;
;                 const float rs = rsqrtf(row_ssq(ssq, 16, 4, row, fq) * (1.f / 1024.f) + EPS);
;                 float r[8];
; #pragma unroll
;                 for (int n = 0; n < 2; ++n)
; #pragma unroll
;                     for (int e = 0; e < 4; ++e) { const float gv = acc[ai][0][m][n][e] * rs, uv = acc[ai][1][m][n][e] * rs; r[n * 4 + e] = gv * fast_sigmoid(gv) * uv; }
;                 u32x4 w; w.x = pk2(r[0], r[1]); w.y = pk2(r[2], r[3]); w.z = pk2(r[4], r[5]); w.w = pk2(r[6], r[7]);
;                 *(u32x4*)(O + (size_t)row * DFF + col0) = w;
	v_cndmask_b32_e32 v196, v196, v197, vcc
	v_rsq_f32_e32 v196, v196
	s_nop 0
	v_mul_f32_e32 v197, 0x45800000, v196
	v_cndmask_b32_e32 v165, v196, v197, vcc
	v_mov_b32_e32 v152, v158
	v_pk_mul_f32 v[126:127], v[126:127], v[152:153] op_sel_hi:[1,0]
	v_pk_mul_f32 v[118:119], v[118:119], v[152:153] op_sel_hi:[1,0]
	v_mul_f32_e32 v145, 0xbfb8aa3b, v126
	v_exp_f32_e32 v145, v145
	v_pk_mul_f32 v[120:121], v[120:121], v[152:153] op_sel_hi:[1,0]
	v_pk_mul_f32 v[122:123], v[122:123], v[152:153] op_sel_hi:[1,0]
	v_pk_mul_f32 v[114:115], v[114:115], v[152:153] op_sel_hi:[1,0]
	v_add_f32_e32 v145, 1.0, v145
	v_rcp_f32_e32 v154, v145
	v_mul_f32_e32 v145, 0xbfb8aa3b, v127
	v_exp_f32_e32 v145, v145
	v_pk_mul_f32 v[116:117], v[116:117], v[152:153] op_sel_hi:[1,0]
	v_add_f32_e32 v145, 1.0, v145
	v_rcp_f32_e32 v155, v145
	s_nop 0
	v_pk_mul_f32 v[126:127], v[126:127], v[154:155]
	s_nop 0
	v_pk_mul_f32 v[118:119], v[118:119], v[126:127]
	v_pk_mul_f32 v[126:127], v[128:129], v[152:153] op_sel_hi:[1,0]
	s_nop 0
	v_mul_f32_e32 v128, 0xbfb8aa3b, v126
	v_mul_f32_e32 v129, 0xbfb8aa3b, v127
	v_exp_f32_e32 v128, v128
	v_exp_f32_e32 v129, v129
	v_add_f32_e32 v128, 1.0, v128
	v_add_f32_e32 v129, 1.0, v129
	v_rcp_f32_e32 v128, v128
	v_rcp_f32_e32 v129, v129
	s_nop 0
	v_pk_mul_f32 v[126:127], v[126:127], v[128:129]
	s_nop 0
	v_pk_mul_f32 v[120:121], v[120:121], v[126:127]
	v_mul_f32_e32 v126, 0xbfb8aa3b, v122
	v_mul_f32_e32 v127, 0xbfb8aa3b, v123
	v_exp_f32_e32 v126, v126
	v_exp_f32_e32 v127, v127
	v_add_f32_e32 v126, 1.0, v126
	v_add_f32_e32 v127, 1.0, v127
	v_rcp_f32_e32 v126, v126
	v_rcp_f32_e32 v127, v127
	s_nop 0
	v_pk_mul_f32 v[122:123], v[122:123], v[126:127]
	s_nop 0
	v_pk_mul_f32 v[122:123], v[114:115], v[122:123]
	v_pk_mul_f32 v[114:115], v[124:125], v[152:153] op_sel_hi:[1,0]
	s_nop 0
	v_mul_f32_e32 v124, 0xbfb8aa3b, v114
	v_mul_f32_e32 v125, 0xbfb8aa3b, v115
	v_exp_f32_e32 v124, v124
	v_exp_f32_e32 v125, v125
	v_add_f32_e32 v124, 1.0, v124
	v_add_f32_e32 v125, 1.0, v125
	v_rcp_f32_e32 v124, v124
	v_rcp_f32_e32 v125, v125
	s_nop 0
	v_pk_mul_f32 v[114:115], v[114:115], v[124:125]
	s_nop 0
	v_pk_mul_f32 v[124:125], v[116:117], v[114:115]
	v_cvt_pk_bf16_f32 v114, v118, v119
	v_cvt_pk_bf16_f32 v115, v120, v121
	v_cvt_pk_bf16_f32 v116, v122, v123
	v_cvt_pk_bf16_f32 v117, v124, v125
	v_mad_i64_i32 v[118:119], s[6:7], v144, s4, v[142:143]
	global_store_dwordx4 v[118:119], v[114:117], off
	s_nop 1
	v_or_b32_e32 v114, 16, v144
	v_mov_b32_e32 v116, v159
	v_pk_mul_f32 v[110:111], v[110:111], v[116:117] op_sel_hi:[1,0]
	v_pk_mul_f32 v[102:103], v[102:103], v[116:117] op_sel_hi:[1,0]
	v_mul_f32_e32 v115, 0xbfb8aa3b, v110
	v_exp_f32_e32 v115, v115
	v_pk_mul_f32 v[104:105], v[104:105], v[116:117] op_sel_hi:[1,0]
	v_pk_mul_f32 v[106:107], v[106:107], v[116:117] op_sel_hi:[1,0]
	v_pk_mul_f32 v[98:99], v[98:99], v[116:117] op_sel_hi:[1,0]
	v_add_f32_e32 v115, 1.0, v115
	v_rcp_f32_e32 v118, v115
	v_mul_f32_e32 v115, 0xbfb8aa3b, v111
	v_exp_f32_e32 v115, v115
	v_pk_mul_f32 v[100:101], v[100:101], v[116:117] op_sel_hi:[1,0]
	v_add_f32_e32 v115, 1.0, v115
	v_rcp_f32_e32 v119, v115
	s_nop 0
	v_pk_mul_f32 v[110:111], v[110:111], v[118:119]
	s_nop 0
	v_pk_mul_f32 v[102:103], v[102:103], v[110:111]
	v_pk_mul_f32 v[110:111], v[112:113], v[116:117] op_sel_hi:[1,0]
	s_nop 0
	v_mul_f32_e32 v112, 0xbfb8aa3b, v110
	v_mul_f32_e32 v113, 0xbfb8aa3b, v111
	v_exp_f32_e32 v112, v112
	v_exp_f32_e32 v113, v113
	v_add_f32_e32 v112, 1.0, v112
	v_add_f32_e32 v113, 1.0, v113
	v_rcp_f32_e32 v112, v112
	v_rcp_f32_e32 v113, v113
	s_nop 0
	v_pk_mul_f32 v[110:111], v[110:111], v[112:113]
	s_nop 0
	v_pk_mul_f32 v[104:105], v[104:105], v[110:111]
	v_mul_f32_e32 v110, 0xbfb8aa3b, v106
	v_mul_f32_e32 v111, 0xbfb8aa3b, v107
	v_exp_f32_e32 v110, v110
	v_exp_f32_e32 v111, v111
	v_add_f32_e32 v110, 1.0, v110
	v_add_f32_e32 v111, 1.0, v111
	v_rcp_f32_e32 v110, v110
	v_rcp_f32_e32 v111, v111
	s_nop 0
	v_pk_mul_f32 v[106:107], v[106:107], v[110:111]
	s_nop 0
	v_pk_mul_f32 v[106:107], v[98:99], v[106:107]
	v_pk_mul_f32 v[98:99], v[108:109], v[116:117] op_sel_hi:[1,0]
	s_nop 0
	v_mul_f32_e32 v108, 0xbfb8aa3b, v98
	v_mul_f32_e32 v109, 0xbfb8aa3b, v99
	v_exp_f32_e32 v108, v108
	v_exp_f32_e32 v109, v109
	v_add_f32_e32 v108, 1.0, v108
	v_add_f32_e32 v109, 1.0, v109
	v_rcp_f32_e32 v108, v108
	v_rcp_f32_e32 v109, v109
	s_nop 0
	v_pk_mul_f32 v[98:99], v[98:99], v[108:109]
	s_nop 0
	v_pk_mul_f32 v[108:109], v[100:101], v[98:99]
	v_cvt_pk_bf16_f32 v98, v102, v103
	v_cvt_pk_bf16_f32 v99, v104, v105
	v_cvt_pk_bf16_f32 v100, v106, v107
	v_cvt_pk_bf16_f32 v101, v108, v109
	v_mad_i64_i32 v[102:103], s[6:7], v114, s4, v[142:143]
	global_store_dwordx4 v[102:103], v[98:101], off
	s_nop 1
	v_or_b32_e32 v98, 32, v144
	v_mov_b32_e32 v100, v160
	v_pk_mul_f32 v[94:95], v[94:95], v[100:101] op_sel_hi:[1,0]
	v_pk_mul_f32 v[86:87], v[86:87], v[100:101] op_sel_hi:[1,0]
	v_mul_f32_e32 v99, 0xbfb8aa3b, v94
	v_exp_f32_e32 v99, v99
	v_pk_mul_f32 v[88:89], v[88:89], v[100:101] op_sel_hi:[1,0]
	v_pk_mul_f32 v[90:91], v[90:91], v[100:101] op_sel_hi:[1,0]
	v_pk_mul_f32 v[82:83], v[82:83], v[100:101] op_sel_hi:[1,0]
	v_add_f32_e32 v99, 1.0, v99
	v_rcp_f32_e32 v102, v99
	v_mul_f32_e32 v99, 0xbfb8aa3b, v95
	v_exp_f32_e32 v99, v99
	v_pk_mul_f32 v[84:85], v[84:85], v[100:101] op_sel_hi:[1,0]
	v_add_f32_e32 v99, 1.0, v99
	v_rcp_f32_e32 v103, v99
	s_nop 0
	v_pk_mul_f32 v[94:95], v[94:95], v[102:103]
	s_nop 0
	v_pk_mul_f32 v[86:87], v[86:87], v[94:95]
	v_pk_mul_f32 v[94:95], v[96:97], v[100:101] op_sel_hi:[1,0]
	s_nop 0
	v_mul_f32_e32 v96, 0xbfb8aa3b, v94
	v_mul_f32_e32 v97, 0xbfb8aa3b, v95
	v_exp_f32_e32 v96, v96
	v_exp_f32_e32 v97, v97
	v_add_f32_e32 v96, 1.0, v96
; __device__ __forceinline__ unsigned pk2(float lo, float hi) { f32x2_t v = {lo, hi}; bf16x2_t b = __builtin_convertvector(v, bf16x2_t); return __builtin_bit_cast(unsigned, b); }
; __device__ __forceinline__ float fast_sigmoid(float x) { return __builtin_amdgcn_rcpf(1.f + __expf(-x)); }
;     __device__ __forceinline__ void operator()(const f32x4 (&acc)[2][2][4][2], const Unit& u, int wr, int wc, int fr, int fq) const {
;         const int row0 = u.pm * BM + wr * 64 + fr, col0 = u.pn * 128 + wc * 32 + 8 * fq;
; #pragma unroll
;         for (int ai = 0; ai < 2; ++ai)
; #pragma unroll
;             for (int m = 0; m < 4; ++m) {
;                 const int row = row0 + ai * HALF + m * 16;
;                 const float rs = rsqrtf(row_ssq(ssq, 16, 4, row, fq) * (1.f / 1024.f) + EPS);
;                 float r[8];
; #pragma unroll
;                 for (int n = 0; n < 2; ++n)
; #pragma unroll
;                     for (int e = 0; e < 4; ++e) { const float gv = acc[ai][0][m][n][e] * rs, uv = acc[ai][1][m][n][e] * rs; r[n * 4 + e] = gv * fast_sigmoid(gv) * uv; }
;                 u32x4 w; w.x = pk2(r[0], r[1]); w.y = pk2(r[2], r[3]); w.z = pk2(r[4], r[5]); w.w = pk2(r[6], r[7]);
;                 *(u32x4*)(O + (size_t)row * DFF + col0) = w;
	v_add_f32_e32 v97, 1.0, v97
	v_rcp_f32_e32 v96, v96
	v_rcp_f32_e32 v97, v97
	s_nop 0
	v_pk_mul_f32 v[94:95], v[94:95], v[96:97]
	s_nop 0
	v_pk_mul_f32 v[88:89], v[88:89], v[94:95]
	v_mul_f32_e32 v94, 0xbfb8aa3b, v90
	v_mul_f32_e32 v95, 0xbfb8aa3b, v91
	v_exp_f32_e32 v94, v94
	v_exp_f32_e32 v95, v95
	v_add_f32_e32 v94, 1.0, v94
	v_add_f32_e32 v95, 1.0, v95
	v_rcp_f32_e32 v94, v94
	v_rcp_f32_e32 v95, v95
	s_nop 0
	v_pk_mul_f32 v[90:91], v[90:91], v[94:95]
	s_nop 0
	v_pk_mul_f32 v[90:91], v[82:83], v[90:91]
	v_pk_mul_f32 v[82:83], v[92:93], v[100:101] op_sel_hi:[1,0]
	s_nop 0
	v_mul_f32_e32 v92, 0xbfb8aa3b, v82
	v_mul_f32_e32 v93, 0xbfb8aa3b, v83
	v_exp_f32_e32 v92, v92
	v_exp_f32_e32 v93, v93
	v_add_f32_e32 v92, 1.0, v92
	v_add_f32_e32 v93, 1.0, v93
	v_rcp_f32_e32 v92, v92
	v_rcp_f32_e32 v93, v93
	s_nop 0
	v_pk_mul_f32 v[82:83], v[82:83], v[92:93]
	s_nop 0
	v_pk_mul_f32 v[92:93], v[84:85], v[82:83]
	v_cvt_pk_bf16_f32 v82, v86, v87
	v_cvt_pk_bf16_f32 v83, v88, v89
	v_cvt_pk_bf16_f32 v84, v90, v91
	v_cvt_pk_bf16_f32 v85, v92, v93
	v_mad_i64_i32 v[86:87], s[6:7], v98, s4, v[142:143]
	global_store_dwordx4 v[86:87], v[82:85], off
	s_nop 1
	v_or_b32_e32 v82, 48, v144
	v_mov_b32_e32 v84, v161
	v_pk_mul_f32 v[78:79], v[78:79], v[84:85] op_sel_hi:[1,0]
	v_pk_mul_f32 v[70:71], v[70:71], v[84:85] op_sel_hi:[1,0]
	v_mul_f32_e32 v83, 0xbfb8aa3b, v78
	v_exp_f32_e32 v83, v83
	v_pk_mul_f32 v[72:73], v[72:73], v[84:85] op_sel_hi:[1,0]
	v_pk_mul_f32 v[74:75], v[74:75], v[84:85] op_sel_hi:[1,0]
	v_pk_mul_f32 v[66:67], v[66:67], v[84:85] op_sel_hi:[1,0]
	v_add_f32_e32 v83, 1.0, v83
	v_rcp_f32_e32 v86, v83
	v_mul_f32_e32 v83, 0xbfb8aa3b, v79
	v_exp_f32_e32 v83, v83
	v_pk_mul_f32 v[68:69], v[68:69], v[84:85] op_sel_hi:[1,0]
	v_add_f32_e32 v83, 1.0, v83
	v_rcp_f32_e32 v87, v83
	s_nop 0
	v_pk_mul_f32 v[78:79], v[78:79], v[86:87]
	s_nop 0
	v_pk_mul_f32 v[70:71], v[70:71], v[78:79]
	v_pk_mul_f32 v[78:79], v[80:81], v[84:85] op_sel_hi:[1,0]
	s_nop 0
	v_mul_f32_e32 v80, 0xbfb8aa3b, v78
	v_mul_f32_e32 v81, 0xbfb8aa3b, v79
	v_exp_f32_e32 v80, v80
	v_exp_f32_e32 v81, v81
	v_add_f32_e32 v80, 1.0, v80
	v_add_f32_e32 v81, 1.0, v81
	v_rcp_f32_e32 v80, v80
	v_rcp_f32_e32 v81, v81
	s_nop 0
	v_pk_mul_f32 v[78:79], v[78:79], v[80:81]
	s_nop 0
	v_pk_mul_f32 v[72:73], v[72:73], v[78:79]
	v_mul_f32_e32 v78, 0xbfb8aa3b, v74
	v_mul_f32_e32 v79, 0xbfb8aa3b, v75
	v_exp_f32_e32 v78, v78
	v_exp_f32_e32 v79, v79
	v_add_f32_e32 v78, 1.0, v78
	v_add_f32_e32 v79, 1.0, v79
	v_rcp_f32_e32 v78, v78
	v_rcp_f32_e32 v79, v79
	s_nop 0
	v_pk_mul_f32 v[74:75], v[74:75], v[78:79]
	s_nop 0
	v_pk_mul_f32 v[74:75], v[66:67], v[74:75]
	v_pk_mul_f32 v[66:67], v[76:77], v[84:85] op_sel_hi:[1,0]
	s_nop 0
	v_mul_f32_e32 v76, 0xbfb8aa3b, v66
	v_mul_f32_e32 v77, 0xbfb8aa3b, v67
	v_exp_f32_e32 v76, v76
	v_exp_f32_e32 v77, v77
	v_add_f32_e32 v76, 1.0, v76
	v_add_f32_e32 v77, 1.0, v77
	v_rcp_f32_e32 v76, v76
	v_rcp_f32_e32 v77, v77
	s_nop 0
	v_pk_mul_f32 v[66:67], v[66:67], v[76:77]
	s_nop 0
	v_pk_mul_f32 v[76:77], v[68:69], v[66:67]
	v_cvt_pk_bf16_f32 v66, v70, v71
	v_cvt_pk_bf16_f32 v67, v72, v73
	v_cvt_pk_bf16_f32 v68, v74, v75
	v_cvt_pk_bf16_f32 v69, v76, v77
	v_mad_i64_i32 v[70:71], s[6:7], v82, s4, v[142:143]
	global_store_dwordx4 v[70:71], v[66:69], off
	s_nop 1
	v_add_u32_e32 v66, 0x80, v144
	v_mov_b32_e32 v68, v162
	v_pk_mul_f32 v[62:63], v[62:63], v[68:69] op_sel_hi:[1,0]
	v_pk_mul_f32 v[54:55], v[54:55], v[68:69] op_sel_hi:[1,0]
	v_mul_f32_e32 v67, 0xbfb8aa3b, v62
	v_exp_f32_e32 v67, v67
	v_pk_mul_f32 v[56:57], v[56:57], v[68:69] op_sel_hi:[1,0]
	v_pk_mul_f32 v[58:59], v[58:59], v[68:69] op_sel_hi:[1,0]
	v_pk_mul_f32 v[50:51], v[50:51], v[68:69] op_sel_hi:[1,0]
	v_add_f32_e32 v67, 1.0, v67
	v_rcp_f32_e32 v70, v67
	v_mul_f32_e32 v67, 0xbfb8aa3b, v63
	v_exp_f32_e32 v67, v67
	v_pk_mul_f32 v[52:53], v[52:53], v[68:69] op_sel_hi:[1,0]
	v_add_f32_e32 v67, 1.0, v67
	v_rcp_f32_e32 v71, v67
	s_nop 0
	v_pk_mul_f32 v[62:63], v[62:63], v[70:71]
	s_nop 0
	v_pk_mul_f32 v[54:55], v[54:55], v[62:63]
	v_pk_mul_f32 v[62:63], v[64:65], v[68:69] op_sel_hi:[1,0]
	s_nop 0
	v_mul_f32_e32 v64, 0xbfb8aa3b, v62
	v_mul_f32_e32 v65, 0xbfb8aa3b, v63
	v_exp_f32_e32 v64, v64
	v_exp_f32_e32 v65, v65
	v_add_f32_e32 v64, 1.0, v64
	v_add_f32_e32 v65, 1.0, v65
	v_rcp_f32_e32 v64, v64
	v_rcp_f32_e32 v65, v65
	s_nop 0
	v_pk_mul_f32 v[62:63], v[62:63], v[64:65]
	s_nop 0
	v_pk_mul_f32 v[56:57], v[56:57], v[62:63]
	v_mul_f32_e32 v62, 0xbfb8aa3b, v58
	v_mul_f32_e32 v63, 0xbfb8aa3b, v59
	v_exp_f32_e32 v62, v62
	v_exp_f32_e32 v63, v63
	v_add_f32_e32 v62, 1.0, v62
	v_add_f32_e32 v63, 1.0, v63
	v_rcp_f32_e32 v62, v62
	v_rcp_f32_e32 v63, v63
	s_nop 0
	v_pk_mul_f32 v[58:59], v[58:59], v[62:63]
	s_nop 0
	v_pk_mul_f32 v[58:59], v[50:51], v[58:59]
	v_pk_mul_f32 v[50:51], v[60:61], v[68:69] op_sel_hi:[1,0]
	s_nop 0
	v_mul_f32_e32 v60, 0xbfb8aa3b, v50
	v_mul_f32_e32 v61, 0xbfb8aa3b, v51
	v_exp_f32_e32 v60, v60
	v_exp_f32_e32 v61, v61
	v_add_f32_e32 v60, 1.0, v60
	v_add_f32_e32 v61, 1.0, v61
	v_rcp_f32_e32 v60, v60
	v_rcp_f32_e32 v61, v61
	s_nop 0
	v_pk_mul_f32 v[50:51], v[50:51], v[60:61]
	s_nop 0
	v_pk_mul_f32 v[60:61], v[52:53], v[50:51]
	v_cvt_pk_bf16_f32 v50, v54, v55
	v_cvt_pk_bf16_f32 v51, v56, v57
	v_cvt_pk_bf16_f32 v52, v58, v59
	v_cvt_pk_bf16_f32 v53, v60, v61
	v_mad_i64_i32 v[54:55], s[6:7], v66, s4, v[142:143]
	global_store_dwordx4 v[54:55], v[50:53], off
	s_nop 1
	v_add_u32_e32 v50, 0x90, v144
	v_mov_b32_e32 v52, v163
	v_pk_mul_f32 v[46:47], v[46:47], v[52:53] op_sel_hi:[1,0]
	v_pk_mul_f32 v[38:39], v[38:39], v[52:53] op_sel_hi:[1,0]
	v_mul_f32_e32 v51, 0xbfb8aa3b, v46
	v_exp_f32_e32 v51, v51
	v_pk_mul_f32 v[40:41], v[40:41], v[52:53] op_sel_hi:[1,0]
; __device__ __forceinline__ unsigned pk2(float lo, float hi) { f32x2_t v = {lo, hi}; bf16x2_t b = __builtin_convertvector(v, bf16x2_t); return __builtin_bit_cast(unsigned, b); }
; __device__ __forceinline__ float fast_sigmoid(float x) { return __builtin_amdgcn_rcpf(1.f + __expf(-x)); }
; #define PG8_BAR __builtin_amdgcn_s_barrier()
; template <class Epi>
; __device__ __forceinline__ void gemm_phase(LAS unsigned char* lds, int wave_s, const Gemm g, const StaticOrder S, const Epi E) {
;     ...
;         if (wr == 0) PG8_BAR;
;         E(acc, cur, wr, wc, fr, fq);
;         if (!has_next) break;
; #pragma unroll
;         for (int a = 0; a < 2; ++a)
; #pragma unroll
;             for (int b = 0; b < 2; ++b)
; #pragma unroll
;                 for (int m = 0; m < 4; ++m)
; #pragma unroll
;                     for (int n = 0; n < 2; ++n) acc[a][b][m][n] = (f32x4){0.f, 0.f, 0.f, 0.f};
;         cur = nxt; cA = nA; cB = nB; ++ui;
;         if (wr == 1) PG8_BAR;
;     __device__ __forceinline__ void operator()(const f32x4 (&acc)[2][2][4][2], const Unit& u, int wr, int wc, int fr, int fq) const {
;         const int row0 = u.pm * BM + wr * 64 + fr, col0 = u.pn * 128 + wc * 32 + 8 * fq;
; #pragma unroll
;         for (int ai = 0; ai < 2; ++ai)
; #pragma unroll
;             for (int m = 0; m < 4; ++m) {
;                 const int row = row0 + ai * HALF + m * 16;
;                 const float rs = rsqrtf(row_ssq(ssq, 16, 4, row, fq) * (1.f / 1024.f) + EPS);
;                 float r[8];
; #pragma unroll
;                 for (int n = 0; n < 2; ++n)
; #pragma unroll
;                     for (int e = 0; e < 4; ++e) { const float gv = acc[ai][0][m][n][e] * rs, uv = acc[ai][1][m][n][e] * rs; r[n * 4 + e] = gv * fast_sigmoid(gv) * uv; }
;                 u32x4 w; w.x = pk2(r[0], r[1]); w.y = pk2(r[2], r[3]); w.z = pk2(r[4], r[5]); w.w = pk2(r[6], r[7]);
;                 *(u32x4*)(O + (size_t)row * DFF + col0) = w;
	v_pk_mul_f32 v[42:43], v[42:43], v[52:53] op_sel_hi:[1,0]
	v_pk_mul_f32 v[34:35], v[34:35], v[52:53] op_sel_hi:[1,0]
	v_add_f32_e32 v51, 1.0, v51
	v_rcp_f32_e32 v54, v51
	v_mul_f32_e32 v51, 0xbfb8aa3b, v47
	v_exp_f32_e32 v51, v51
	v_pk_mul_f32 v[36:37], v[36:37], v[52:53] op_sel_hi:[1,0]
	v_add_f32_e32 v51, 1.0, v51
	v_rcp_f32_e32 v55, v51
	s_nop 0
	v_pk_mul_f32 v[46:47], v[46:47], v[54:55]
	s_nop 0
	v_pk_mul_f32 v[38:39], v[38:39], v[46:47]
	v_pk_mul_f32 v[46:47], v[48:49], v[52:53] op_sel_hi:[1,0]
	s_nop 0
	v_mul_f32_e32 v48, 0xbfb8aa3b, v46
	v_mul_f32_e32 v49, 0xbfb8aa3b, v47
	v_exp_f32_e32 v48, v48
	v_exp_f32_e32 v49, v49
	v_add_f32_e32 v48, 1.0, v48
	v_add_f32_e32 v49, 1.0, v49
	v_rcp_f32_e32 v48, v48
	v_rcp_f32_e32 v49, v49
	s_nop 0
	v_pk_mul_f32 v[46:47], v[46:47], v[48:49]
	s_nop 0
	v_pk_mul_f32 v[40:41], v[40:41], v[46:47]
	v_mul_f32_e32 v46, 0xbfb8aa3b, v42
	v_mul_f32_e32 v47, 0xbfb8aa3b, v43
	v_exp_f32_e32 v46, v46
	v_exp_f32_e32 v47, v47
	v_add_f32_e32 v46, 1.0, v46
	v_add_f32_e32 v47, 1.0, v47
	v_rcp_f32_e32 v46, v46
	v_rcp_f32_e32 v47, v47
	s_nop 0
	v_pk_mul_f32 v[42:43], v[42:43], v[46:47]
	s_nop 0
	v_pk_mul_f32 v[42:43], v[34:35], v[42:43]
	v_pk_mul_f32 v[34:35], v[44:45], v[52:53] op_sel_hi:[1,0]
	s_nop 0
	v_mul_f32_e32 v44, 0xbfb8aa3b, v34
	v_mul_f32_e32 v45, 0xbfb8aa3b, v35
	v_exp_f32_e32 v44, v44
	v_exp_f32_e32 v45, v45
	v_add_f32_e32 v44, 1.0, v44
	v_add_f32_e32 v45, 1.0, v45
	v_rcp_f32_e32 v44, v44
	v_rcp_f32_e32 v45, v45
	s_nop 0
	v_pk_mul_f32 v[34:35], v[34:35], v[44:45]
	s_nop 0
	v_pk_mul_f32 v[44:45], v[36:37], v[34:35]
	v_cvt_pk_bf16_f32 v34, v38, v39
	v_cvt_pk_bf16_f32 v35, v40, v41
	v_cvt_pk_bf16_f32 v36, v42, v43
	v_cvt_pk_bf16_f32 v37, v44, v45
	v_mad_i64_i32 v[38:39], s[6:7], v50, s4, v[142:143]
	global_store_dwordx4 v[38:39], v[34:37], off
	s_nop 1
	v_add_u32_e32 v34, 0xa0, v144
	v_mov_b32_e32 v36, v164
	v_pk_mul_f32 v[30:31], v[30:31], v[36:37] op_sel_hi:[1,0]
	v_pk_mul_f32 v[22:23], v[22:23], v[36:37] op_sel_hi:[1,0]
	v_mul_f32_e32 v35, 0xbfb8aa3b, v30
	v_exp_f32_e32 v35, v35
	v_pk_mul_f32 v[24:25], v[24:25], v[36:37] op_sel_hi:[1,0]
	v_pk_mul_f32 v[26:27], v[26:27], v[36:37] op_sel_hi:[1,0]
	v_pk_mul_f32 v[18:19], v[18:19], v[36:37] op_sel_hi:[1,0]
	v_add_f32_e32 v35, 1.0, v35
	v_rcp_f32_e32 v38, v35
	v_mul_f32_e32 v35, 0xbfb8aa3b, v31
	v_exp_f32_e32 v35, v35
	v_pk_mul_f32 v[20:21], v[20:21], v[36:37] op_sel_hi:[1,0]
	v_add_f32_e32 v35, 1.0, v35
	v_rcp_f32_e32 v39, v35
	s_nop 0
	v_pk_mul_f32 v[30:31], v[30:31], v[38:39]
	s_nop 0
	v_pk_mul_f32 v[22:23], v[22:23], v[30:31]
	v_pk_mul_f32 v[30:31], v[32:33], v[36:37] op_sel_hi:[1,0]
	s_nop 0
	v_mul_f32_e32 v32, 0xbfb8aa3b, v30
	v_mul_f32_e32 v33, 0xbfb8aa3b, v31
	v_exp_f32_e32 v32, v32
	v_exp_f32_e32 v33, v33
	v_add_f32_e32 v32, 1.0, v32
	v_add_f32_e32 v33, 1.0, v33
	v_rcp_f32_e32 v32, v32
	v_rcp_f32_e32 v33, v33
	s_nop 0
	v_pk_mul_f32 v[30:31], v[30:31], v[32:33]
	s_nop 0
	v_pk_mul_f32 v[24:25], v[24:25], v[30:31]
	v_mul_f32_e32 v30, 0xbfb8aa3b, v26
	v_mul_f32_e32 v31, 0xbfb8aa3b, v27
	v_exp_f32_e32 v30, v30
	v_exp_f32_e32 v31, v31
	v_add_f32_e32 v30, 1.0, v30
	v_add_f32_e32 v31, 1.0, v31
	v_rcp_f32_e32 v30, v30
	v_rcp_f32_e32 v31, v31
	s_nop 0
	v_pk_mul_f32 v[26:27], v[26:27], v[30:31]
	s_nop 0
	v_pk_mul_f32 v[26:27], v[18:19], v[26:27]
	v_pk_mul_f32 v[18:19], v[28:29], v[36:37] op_sel_hi:[1,0]
	s_nop 0
	v_mul_f32_e32 v28, 0xbfb8aa3b, v18
	v_mul_f32_e32 v29, 0xbfb8aa3b, v19
	v_exp_f32_e32 v28, v28
	v_exp_f32_e32 v29, v29
	v_add_f32_e32 v28, 1.0, v28
	v_add_f32_e32 v29, 1.0, v29
	v_rcp_f32_e32 v28, v28
	v_rcp_f32_e32 v29, v29
	s_nop 0
	v_pk_mul_f32 v[18:19], v[18:19], v[28:29]
	s_nop 0
	v_pk_mul_f32 v[28:29], v[20:21], v[18:19]
	v_cvt_pk_bf16_f32 v18, v22, v23
	v_cvt_pk_bf16_f32 v19, v24, v25
	v_cvt_pk_bf16_f32 v20, v26, v27
	v_cvt_pk_bf16_f32 v21, v28, v29
	v_mad_i64_i32 v[22:23], s[6:7], v34, s4, v[142:143]
	global_store_dwordx4 v[22:23], v[18:21], off
	s_nop 1
	v_add_u32_e32 v18, 0xb0, v144
	v_mov_b32_e32 v20, v165
	v_pk_mul_f32 v[14:15], v[14:15], v[20:21] op_sel_hi:[1,0]
	v_pk_mul_f32 v[6:7], v[6:7], v[20:21] op_sel_hi:[1,0]
	v_mul_f32_e32 v19, 0xbfb8aa3b, v14
	v_exp_f32_e32 v19, v19
	v_pk_mul_f32 v[8:9], v[8:9], v[20:21] op_sel_hi:[1,0]
	v_pk_mul_f32 v[10:11], v[10:11], v[20:21] op_sel_hi:[1,0]
	v_pk_mul_f32 v[2:3], v[2:3], v[20:21] op_sel_hi:[1,0]
	v_add_f32_e32 v19, 1.0, v19
	v_rcp_f32_e32 v22, v19
	v_mul_f32_e32 v19, 0xbfb8aa3b, v15
	v_exp_f32_e32 v19, v19
	v_pk_mul_f32 v[4:5], v[4:5], v[20:21] op_sel_hi:[1,0]
	s_andn2_b64 vcc, exec, s[0:1]
	v_add_f32_e32 v19, 1.0, v19
	v_rcp_f32_e32 v23, v19
	s_nop 0
	v_pk_mul_f32 v[14:15], v[14:15], v[22:23]
	s_nop 0
	v_pk_mul_f32 v[6:7], v[6:7], v[14:15]
	v_pk_mul_f32 v[14:15], v[16:17], v[20:21] op_sel_hi:[1,0]
	s_nop 0
	v_mul_f32_e32 v16, 0xbfb8aa3b, v14
	v_mul_f32_e32 v17, 0xbfb8aa3b, v15
	v_exp_f32_e32 v16, v16
	v_exp_f32_e32 v17, v17
	v_add_f32_e32 v16, 1.0, v16
	v_add_f32_e32 v17, 1.0, v17
	v_rcp_f32_e32 v16, v16
	v_rcp_f32_e32 v17, v17
	s_nop 0
	v_pk_mul_f32 v[14:15], v[14:15], v[16:17]
	s_nop 0
	v_pk_mul_f32 v[8:9], v[8:9], v[14:15]
	v_mul_f32_e32 v14, 0xbfb8aa3b, v10
	v_mul_f32_e32 v15, 0xbfb8aa3b, v11
	v_exp_f32_e32 v14, v14
	v_exp_f32_e32 v15, v15
	v_add_f32_e32 v14, 1.0, v14
	v_add_f32_e32 v15, 1.0, v15
	v_rcp_f32_e32 v14, v14
	v_rcp_f32_e32 v15, v15
	s_nop 0
	v_pk_mul_f32 v[10:11], v[10:11], v[14:15]
	s_nop 0
	v_pk_mul_f32 v[10:11], v[2:3], v[10:11]
	v_pk_mul_f32 v[2:3], v[12:13], v[20:21] op_sel_hi:[1,0]
	s_nop 0
	v_mul_f32_e32 v12, 0xbfb8aa3b, v2
	v_mul_f32_e32 v13, 0xbfb8aa3b, v3
	v_exp_f32_e32 v12, v12
	v_exp_f32_e32 v13, v13
	v_add_f32_e32 v12, 1.0, v12
	v_add_f32_e32 v13, 1.0, v13
	v_rcp_f32_e32 v12, v12
	v_rcp_f32_e32 v13, v13
	s_nop 0
	v_pk_mul_f32 v[2:3], v[2:3], v[12:13]
	s_nop 0
	v_pk_mul_f32 v[12:13], v[4:5], v[2:3]
	v_cvt_pk_bf16_f32 v2, v6, v7
	v_cvt_pk_bf16_f32 v3, v8, v9
	v_cvt_pk_bf16_f32 v4, v10, v11
	v_cvt_pk_bf16_f32 v5, v12, v13
	v_mad_i64_i32 v[6:7], s[6:7], v18, s4, v[142:143]
	global_store_dwordx4 v[6:7], v[2:5], off
	s_cbranch_vccnz .LBB0_161
	s_andn2_b64 vcc, exec, s[12:13]
	s_cbranch_vccnz .LBB0_160
	s_barrier
	s_branch .LBB0_160

; __device__ __forceinline__ float row_ssq(const float* part, int pitch, int n4, int row, int fq) {
;     f32x4 v = (f32x4){0.f, 0.f, 0.f, 0.f};
;     if (fq < n4) v = *(const f32x4*)(part + (size_t)row * pitch + 4 * fq);
;     float s = (v[0] + v[1]) + (v[2] + v[3]);
;     s += __shfl_xor(s, 16); s += __shfl_xor(s, 32);
;     return s;
; }
;     __device__ __forceinline__ void operator()(const f32x4 (&acc)[2][2][4][2], const Unit& u, int wr, int wc, int fr, int fq) const {
;         const int row0 = u.pm * BM + wr * 64 + fr, col0 = u.pn * 128 + wc * 32 + 8 * fq;
; #pragma unroll
;         for (int ai = 0; ai < 2; ++ai)
; #pragma unroll
;             for (int m = 0; m < 4; ++m) {
;                 const int row = row0 + ai * HALF + m * 16;
;                 const float rs = rsqrtf(row_ssq(ssq, 16, 4, row, fq) * (1.f / 1024.f) + EPS);
.LBB0_1154:
	v_and_b32_e32 v145, 64, v241
	v_xor_b32_e32 v143, 16, v241
	v_add_u32_e32 v145, 64, v145
	v_cmp_lt_i32_e32 vcc, v143, v145
	v_lshl_add_u32 v144, s39, 8, v146
	v_lshl_or_b32 v142, s4, 7, v148
	v_cndmask_b32_e32 v143, v241, v143, vcc
	v_lshlrev_b32_e32 v150, 2, v143
	v_xor_b32_e32 v143, 32, v241
	v_cmp_lt_i32_e32 vcc, v143, v145
	v_ashrrev_i32_e32 v145, 31, v144
	v_lshlrev_b64 v[166:167], 6, v[144:145]
	v_lshl_add_u64 v[166:167], v[136:137], 0, v[166:167]
	global_load_dwordx4 v[168:171], v[166:167], off
	global_load_dwordx4 v[172:175], v[166:167], off offset:1024
	global_load_dwordx4 v[176:179], v[166:167], off offset:2048
	global_load_dwordx4 v[180:183], v[166:167], off offset:3072
	v_cndmask_b32_e32 v143, v241, v143, vcc
	v_add_co_u32_e32 v166, vcc, 0x2000, v166
	v_lshlrev_b32_e32 v151, 2, v143
	v_addc_co_u32_e32 v167, vcc, 0, v167, vcc
	global_load_dwordx4 v[184:187], v[166:167], off
	global_load_dwordx4 v[188:191], v[166:167], off offset:1024
	global_load_dwordx4 v[192:195], v[166:167], off offset:2048
	global_load_dwordx4 v[196:199], v[166:167], off offset:3072
	v_ashrrev_i32_e32 v143, 31, v142
	v_lshl_add_u64 v[142:143], v[142:143], 1, s[96:97]
	s_movk_i32 s4, 0x1600
	s_mov_b64 s[22:23], -1
	s_waitcnt vmcnt(7)
	v_add_f32_e32 v168, v169, v168
	v_add_f32_e32 v170, v170, v171
	v_add_f32_e32 v168, v168, v170
	ds_bpermute_b32 v169, v150, v168
	s_waitcnt vmcnt(6)
	v_add_f32_e32 v172, v173, v172
	v_add_f32_e32 v174, v174, v175
	v_add_f32_e32 v172, v172, v174
	ds_bpermute_b32 v173, v150, v172
	s_waitcnt vmcnt(5)
	v_add_f32_e32 v176, v177, v176
	v_add_f32_e32 v178, v178, v179
	v_add_f32_e32 v176, v176, v178
	ds_bpermute_b32 v177, v150, v176
	s_waitcnt vmcnt(4)
	v_add_f32_e32 v180, v181, v180
	v_add_f32_e32 v182, v182, v183
	v_add_f32_e32 v180, v180, v182
	ds_bpermute_b32 v181, v150, v180
	s_waitcnt vmcnt(3)
	v_add_f32_e32 v184, v185, v184
	v_add_f32_e32 v186, v186, v187
	v_add_f32_e32 v184, v184, v186
	ds_bpermute_b32 v185, v150, v184
	s_waitcnt vmcnt(2)
	v_add_f32_e32 v188, v189, v188
	v_add_f32_e32 v190, v190, v191
	v_add_f32_e32 v188, v188, v190
	ds_bpermute_b32 v189, v150, v188
	s_waitcnt vmcnt(1)
	v_add_f32_e32 v192, v193, v192
	v_add_f32_e32 v194, v194, v195
	v_add_f32_e32 v192, v192, v194
	ds_bpermute_b32 v193, v150, v192
	s_waitcnt vmcnt(0)
	v_add_f32_e32 v196, v197, v196
	v_add_f32_e32 v198, v198, v199
	v_add_f32_e32 v196, v196, v198
	ds_bpermute_b32 v197, v150, v196
	s_waitcnt lgkmcnt(7)
	v_add_f32_e32 v168, v168, v169
	ds_bpermute_b32 v169, v151, v168
	s_waitcnt lgkmcnt(7)
	v_add_f32_e32 v172, v172, v173
	ds_bpermute_b32 v173, v151, v172
	s_waitcnt lgkmcnt(7)
	v_add_f32_e32 v176, v176, v177
	ds_bpermute_b32 v177, v151, v176
	s_waitcnt lgkmcnt(7)
	v_add_f32_e32 v180, v180, v181
	ds_bpermute_b32 v181, v151, v180
	s_waitcnt lgkmcnt(7)
	v_add_f32_e32 v184, v184, v185
	ds_bpermute_b32 v185, v151, v184
	s_waitcnt lgkmcnt(7)
	v_add_f32_e32 v188, v188, v189
	ds_bpermute_b32 v189, v151, v188
	s_waitcnt lgkmcnt(7)
	v_add_f32_e32 v192, v192, v193
	ds_bpermute_b32 v193, v151, v192
	s_waitcnt lgkmcnt(7)
	v_add_f32_e32 v196, v196, v197
	ds_bpermute_b32 v197, v151, v196
	s_waitcnt lgkmcnt(7)
	v_add_f32_e32 v168, v168, v169
	v_fmamk_f32 v168, v168, 0x3a800000, v239
	s_waitcnt lgkmcnt(6)
	v_add_f32_e32 v172, v172, v173
	v_fmamk_f32 v172, v172, 0x3a800000, v239
	s_waitcnt lgkmcnt(5)
	v_add_f32_e32 v176, v176, v177
	v_fmamk_f32 v176, v176, 0x3a800000, v239
	s_waitcnt lgkmcnt(4)
	v_add_f32_e32 v180, v180, v181
	v_fmamk_f32 v180, v180, 0x3a800000, v239
	s_waitcnt lgkmcnt(3)
	v_add_f32_e32 v184, v184, v185
	v_fmamk_f32 v184, v184, 0x3a800000, v239
	s_waitcnt lgkmcnt(2)
	v_add_f32_e32 v188, v188, v189
	v_fmamk_f32 v188, v188, 0x3a800000, v239
	s_waitcnt lgkmcnt(1)
	v_add_f32_e32 v192, v192, v193
	v_fmamk_f32 v192, v192, 0x3a800000, v239
	s_waitcnt lgkmcnt(0)
	v_add_f32_e32 v196, v196, v197
	v_fmamk_f32 v196, v196, 0x3a800000, v239
	v_cmp_gt_f32_e32 vcc, s55, v168
	v_mul_f32_e32 v169, 0x4b800000, v168
	s_nop 0
	v_cndmask_b32_e32 v168, v168, v169, vcc
	v_rsq_f32_e32 v168, v168
	s_nop 0
	v_mul_f32_e32 v169, 0x45800000, v168
	v_cndmask_b32_e32 v158, v168, v169, vcc
	v_cmp_gt_f32_e32 vcc, s55, v172
	v_mul_f32_e32 v173, 0x4b800000, v172
	s_nop 0
	v_cndmask_b32_e32 v172, v172, v173, vcc
	v_rsq_f32_e32 v172, v172
	s_nop 0
	v_mul_f32_e32 v173, 0x45800000, v172
	v_cndmask_b32_e32 v159, v172, v173, vcc
	v_cmp_gt_f32_e32 vcc, s55, v176
	v_mul_f32_e32 v177, 0x4b800000, v176
	s_nop 0
	v_cndmask_b32_e32 v176, v176, v177, vcc
	v_rsq_f32_e32 v176, v176
	s_nop 0
	v_mul_f32_e32 v177, 0x45800000, v176
	v_cndmask_b32_e32 v160, v176, v177, vcc
	v_cmp_gt_f32_e32 vcc, s55, v180
	v_mul_f32_e32 v181, 0x4b800000, v180
	s_nop 0
	v_cndmask_b32_e32 v180, v180, v181, vcc
	v_rsq_f32_e32 v180, v180
	s_nop 0
	v_mul_f32_e32 v181, 0x45800000, v180
	v_cndmask_b32_e32 v161, v180, v181, vcc
	v_cmp_gt_f32_e32 vcc, s55, v184
	v_mul_f32_e32 v185, 0x4b800000, v184
	s_nop 0
	v_cndmask_b32_e32 v184, v184, v185, vcc
	v_rsq_f32_e32 v184, v184
	s_nop 0
	v_mul_f32_e32 v185, 0x45800000, v184
	v_cndmask_b32_e32 v162, v184, v185, vcc
	v_cmp_gt_f32_e32 vcc, s55, v188
	v_mul_f32_e32 v189, 0x4b800000, v188
	s_nop 0
	v_cndmask_b32_e32 v188, v188, v189, vcc
	v_rsq_f32_e32 v188, v188
	s_nop 0
	v_mul_f32_e32 v189, 0x45800000, v188
	v_cndmask_b32_e32 v163, v188, v189, vcc
	v_cmp_gt_f32_e32 vcc, s55, v192
	v_mul_f32_e32 v193, 0x4b800000, v192
	s_nop 0
	v_cndmask_b32_e32 v192, v192, v193, vcc
	v_rsq_f32_e32 v192, v192
	s_nop 0
	v_mul_f32_e32 v193, 0x45800000, v192
	v_cndmask_b32_e32 v164, v192, v193, vcc
	v_cmp_gt_f32_e32 vcc, s55, v196
	v_mul_f32_e32 v197, 0x4b800000, v196
	s_nop 0
; __device__ __forceinline__ unsigned pk2(float lo, float hi) { f32x2_t v = {lo, hi}; bf16x2_t b = __builtin_convertvector(v, bf16x2_t); return __builtin_bit_cast(unsigned, b); }
; __device__ __forceinline__ float fast_sigmoid(float x) { return __builtin_amdgcn_rcpf(1.f + __expf(-x)); }
;     __device__ __forceinline__ void operator()(const f32x4 (&acc)[2][2][4][2], const Unit& u, int wr, int wc, int fr, int fq) const {
;         const int row0 = u.pm * BM + wr * 64 + fr, col0 = u.pn * 128 + wc * 32 + 8 * fq;
; #pragma unroll
;         for (int ai = 0; ai < 2; ++ai)
; #pragma unroll
;             for (int m = 0; m < 4; ++m) {
;                 const int row = row0 + ai * HALF + m * 16;
;                 const float rs = rsqrtf(row_ssq(ssq, 16, 4, row, fq) * (1.f / 1024.f) + EPS);
;                 float r[8];
; #pragma unroll
;                 for (int n = 0; n < 2; ++n)
; #pragma unroll
;                     for (int e = 0; e < 4; ++e) { const float gv = acc[ai][0][m][n][e] * rs, uv = acc[ai][1][m][n][e] * rs; r[n * 4 + e] = gv * fast_sigmoid(gv) * uv; }
;                 u32x4 w; w.x = pk2(r[0], r[1]); w.y = pk2(r[2], r[3]); w.z = pk2(r[4], r[5]); w.w = pk2(r[6], r[7]);
;                 *(u32x4*)(O + (size_t)row * DFF + col0) = w;
	v_cndmask_b32_e32 v196, v196, v197, vcc
	v_rsq_f32_e32 v196, v196
	s_nop 0
	v_mul_f32_e32 v197, 0x45800000, v196
	v_cndmask_b32_e32 v165, v196, v197, vcc
	v_mov_b32_e32 v152, v158
	v_pk_mul_f32 v[126:127], v[126:127], v[152:153] op_sel_hi:[1,0]
	v_pk_mul_f32 v[118:119], v[118:119], v[152:153] op_sel_hi:[1,0]
	v_mul_f32_e32 v145, 0xbfb8aa3b, v126
	v_exp_f32_e32 v145, v145
	v_pk_mul_f32 v[120:121], v[120:121], v[152:153] op_sel_hi:[1,0]
	v_pk_mul_f32 v[122:123], v[122:123], v[152:153] op_sel_hi:[1,0]
	v_pk_mul_f32 v[114:115], v[114:115], v[152:153] op_sel_hi:[1,0]
	v_add_f32_e32 v145, 1.0, v145
	v_rcp_f32_e32 v154, v145
	v_mul_f32_e32 v145, 0xbfb8aa3b, v127
	v_exp_f32_e32 v145, v145
	v_pk_mul_f32 v[116:117], v[116:117], v[152:153] op_sel_hi:[1,0]
	v_add_f32_e32 v145, 1.0, v145
	v_rcp_f32_e32 v155, v145
	s_nop 0
	v_pk_mul_f32 v[126:127], v[126:127], v[154:155]
	s_nop 0
	v_pk_mul_f32 v[118:119], v[118:119], v[126:127]
	v_pk_mul_f32 v[126:127], v[128:129], v[152:153] op_sel_hi:[1,0]
	s_nop 0
	v_mul_f32_e32 v128, 0xbfb8aa3b, v126
	v_mul_f32_e32 v129, 0xbfb8aa3b, v127
	v_exp_f32_e32 v128, v128
	v_exp_f32_e32 v129, v129
	v_add_f32_e32 v128, 1.0, v128
	v_add_f32_e32 v129, 1.0, v129
	v_rcp_f32_e32 v128, v128
	v_rcp_f32_e32 v129, v129
	s_nop 0
	v_pk_mul_f32 v[126:127], v[126:127], v[128:129]
	s_nop 0
	v_pk_mul_f32 v[120:121], v[120:121], v[126:127]
	v_mul_f32_e32 v126, 0xbfb8aa3b, v122
	v_mul_f32_e32 v127, 0xbfb8aa3b, v123
	v_exp_f32_e32 v126, v126
	v_exp_f32_e32 v127, v127
	v_add_f32_e32 v126, 1.0, v126
	v_add_f32_e32 v127, 1.0, v127
	v_rcp_f32_e32 v126, v126
	v_rcp_f32_e32 v127, v127
	s_nop 0
	v_pk_mul_f32 v[122:123], v[122:123], v[126:127]
	s_nop 0
	v_pk_mul_f32 v[122:123], v[114:115], v[122:123]
	v_pk_mul_f32 v[114:115], v[124:125], v[152:153] op_sel_hi:[1,0]
	s_nop 0
	v_mul_f32_e32 v124, 0xbfb8aa3b, v114
	v_mul_f32_e32 v125, 0xbfb8aa3b, v115
	v_exp_f32_e32 v124, v124
	v_exp_f32_e32 v125, v125
	v_add_f32_e32 v124, 1.0, v124
	v_add_f32_e32 v125, 1.0, v125
	v_rcp_f32_e32 v124, v124
	v_rcp_f32_e32 v125, v125
	s_nop 0
	v_pk_mul_f32 v[114:115], v[114:115], v[124:125]
	s_nop 0
	v_pk_mul_f32 v[124:125], v[116:117], v[114:115]
	v_cvt_pk_bf16_f32 v114, v118, v119
	v_cvt_pk_bf16_f32 v115, v120, v121
	v_cvt_pk_bf16_f32 v116, v122, v123
	v_cvt_pk_bf16_f32 v117, v124, v125
	v_mad_i64_i32 v[118:119], s[6:7], v144, s4, v[142:143]
	global_store_dwordx4 v[118:119], v[114:117], off
	s_nop 1
	v_or_b32_e32 v114, 16, v144
	v_mov_b32_e32 v116, v159
	v_pk_mul_f32 v[110:111], v[110:111], v[116:117] op_sel_hi:[1,0]
	v_pk_mul_f32 v[102:103], v[102:103], v[116:117] op_sel_hi:[1,0]
	v_mul_f32_e32 v115, 0xbfb8aa3b, v110
	v_exp_f32_e32 v115, v115
	v_pk_mul_f32 v[104:105], v[104:105], v[116:117] op_sel_hi:[1,0]
	v_pk_mul_f32 v[106:107], v[106:107], v[116:117] op_sel_hi:[1,0]
	v_pk_mul_f32 v[98:99], v[98:99], v[116:117] op_sel_hi:[1,0]
	v_add_f32_e32 v115, 1.0, v115
	v_rcp_f32_e32 v118, v115
	v_mul_f32_e32 v115, 0xbfb8aa3b, v111
	v_exp_f32_e32 v115, v115
	v_pk_mul_f32 v[100:101], v[100:101], v[116:117] op_sel_hi:[1,0]
	v_add_f32_e32 v115, 1.0, v115
	v_rcp_f32_e32 v119, v115
	s_nop 0
	v_pk_mul_f32 v[110:111], v[110:111], v[118:119]
	s_nop 0
	v_pk_mul_f32 v[102:103], v[102:103], v[110:111]
	v_pk_mul_f32 v[110:111], v[112:113], v[116:117] op_sel_hi:[1,0]
	s_nop 0
	v_mul_f32_e32 v112, 0xbfb8aa3b, v110
	v_mul_f32_e32 v113, 0xbfb8aa3b, v111
	v_exp_f32_e32 v112, v112
	v_exp_f32_e32 v113, v113
	v_add_f32_e32 v112, 1.0, v112
	v_add_f32_e32 v113, 1.0, v113
	v_rcp_f32_e32 v112, v112
	v_rcp_f32_e32 v113, v113
	s_nop 0
	v_pk_mul_f32 v[110:111], v[110:111], v[112:113]
	s_nop 0
	v_pk_mul_f32 v[104:105], v[104:105], v[110:111]
	v_mul_f32_e32 v110, 0xbfb8aa3b, v106
	v_mul_f32_e32 v111, 0xbfb8aa3b, v107
	v_exp_f32_e32 v110, v110
	v_exp_f32_e32 v111, v111
	v_add_f32_e32 v110, 1.0, v110
	v_add_f32_e32 v111, 1.0, v111
	v_rcp_f32_e32 v110, v110
	v_rcp_f32_e32 v111, v111
	s_nop 0
	v_pk_mul_f32 v[106:107], v[106:107], v[110:111]
	s_nop 0
	v_pk_mul_f32 v[106:107], v[98:99], v[106:107]
	v_pk_mul_f32 v[98:99], v[108:109], v[116:117] op_sel_hi:[1,0]
	s_nop 0
	v_mul_f32_e32 v108, 0xbfb8aa3b, v98
	v_mul_f32_e32 v109, 0xbfb8aa3b, v99
	v_exp_f32_e32 v108, v108
	v_exp_f32_e32 v109, v109
	v_add_f32_e32 v108, 1.0, v108
	v_add_f32_e32 v109, 1.0, v109
	v_rcp_f32_e32 v108, v108
	v_rcp_f32_e32 v109, v109
	s_nop 0
	v_pk_mul_f32 v[98:99], v[98:99], v[108:109]
	s_nop 0
	v_pk_mul_f32 v[108:109], v[100:101], v[98:99]
	v_cvt_pk_bf16_f32 v98, v102, v103
	v_cvt_pk_bf16_f32 v99, v104, v105
	v_cvt_pk_bf16_f32 v100, v106, v107
	v_cvt_pk_bf16_f32 v101, v108, v109
	v_mad_i64_i32 v[102:103], s[6:7], v114, s4, v[142:143]
	global_store_dwordx4 v[102:103], v[98:101], off
	s_nop 1
	v_or_b32_e32 v98, 32, v144
	v_mov_b32_e32 v100, v160
	v_pk_mul_f32 v[94:95], v[94:95], v[100:101] op_sel_hi:[1,0]
	v_pk_mul_f32 v[86:87], v[86:87], v[100:101] op_sel_hi:[1,0]
	v_mul_f32_e32 v99, 0xbfb8aa3b, v94
	v_exp_f32_e32 v99, v99
	v_pk_mul_f32 v[88:89], v[88:89], v[100:101] op_sel_hi:[1,0]
	v_pk_mul_f32 v[90:91], v[90:91], v[100:101] op_sel_hi:[1,0]
	v_pk_mul_f32 v[82:83], v[82:83], v[100:101] op_sel_hi:[1,0]
	v_add_f32_e32 v99, 1.0, v99
	v_rcp_f32_e32 v102, v99
	v_mul_f32_e32 v99, 0xbfb8aa3b, v95
	v_exp_f32_e32 v99, v99
	v_pk_mul_f32 v[84:85], v[84:85], v[100:101] op_sel_hi:[1,0]
	v_add_f32_e32 v99, 1.0, v99
	v_rcp_f32_e32 v103, v99
	s_nop 0
	v_pk_mul_f32 v[94:95], v[94:95], v[102:103]
	s_nop 0
	v_pk_mul_f32 v[86:87], v[86:87], v[94:95]
	v_pk_mul_f32 v[94:95], v[96:97], v[100:101] op_sel_hi:[1,0]
	s_nop 0
	v_mul_f32_e32 v96, 0xbfb8aa3b, v94
	v_mul_f32_e32 v97, 0xbfb8aa3b, v95
	v_exp_f32_e32 v96, v96
	v_exp_f32_e32 v97, v97
	v_add_f32_e32 v96, 1.0, v96
; __device__ __forceinline__ unsigned pk2(float lo, float hi) { f32x2_t v = {lo, hi}; bf16x2_t b = __builtin_convertvector(v, bf16x2_t); return __builtin_bit_cast(unsigned, b); }
; __device__ __forceinline__ float fast_sigmoid(float x) { return __builtin_amdgcn_rcpf(1.f + __expf(-x)); }
;     __device__ __forceinline__ void operator()(const f32x4 (&acc)[2][2][4][2], const Unit& u, int wr, int wc, int fr, int fq) const {
;         const int row0 = u.pm * BM + wr * 64 + fr, col0 = u.pn * 128 + wc * 32 + 8 * fq;
; #pragma unroll
;         for (int ai = 0; ai < 2; ++ai)
; #pragma unroll
;             for (int m = 0; m < 4; ++m) {
;                 const int row = row0 + ai * HALF + m * 16;
;                 const float rs = rsqrtf(row_ssq(ssq, 16, 4, row, fq) * (1.f / 1024.f) + EPS);
;                 float r[8];
; #pragma unroll
;                 for (int n = 0; n < 2; ++n)
; #pragma unroll
;                     for (int e = 0; e < 4; ++e) { const float gv = acc[ai][0][m][n][e] * rs, uv = acc[ai][1][m][n][e] * rs; r[n * 4 + e] = gv * fast_sigmoid(gv) * uv; }
;                 u32x4 w; w.x = pk2(r[0], r[1]); w.y = pk2(r[2], r[3]); w.z = pk2(r[4], r[5]); w.w = pk2(r[6], r[7]);
;                 *(u32x4*)(O + (size_t)row * DFF + col0) = w;
	v_add_f32_e32 v97, 1.0, v97
	v_rcp_f32_e32 v96, v96
	v_rcp_f32_e32 v97, v97
	s_nop 0
	v_pk_mul_f32 v[94:95], v[94:95], v[96:97]
	s_nop 0
	v_pk_mul_f32 v[88:89], v[88:89], v[94:95]
	v_mul_f32_e32 v94, 0xbfb8aa3b, v90
	v_mul_f32_e32 v95, 0xbfb8aa3b, v91
	v_exp_f32_e32 v94, v94
	v_exp_f32_e32 v95, v95
	v_add_f32_e32 v94, 1.0, v94
	v_add_f32_e32 v95, 1.0, v95
	v_rcp_f32_e32 v94, v94
	v_rcp_f32_e32 v95, v95
	s_nop 0
	v_pk_mul_f32 v[90:91], v[90:91], v[94:95]
	s_nop 0
	v_pk_mul_f32 v[90:91], v[82:83], v[90:91]
	v_pk_mul_f32 v[82:83], v[92:93], v[100:101] op_sel_hi:[1,0]
	s_nop 0
	v_mul_f32_e32 v92, 0xbfb8aa3b, v82
	v_mul_f32_e32 v93, 0xbfb8aa3b, v83
	v_exp_f32_e32 v92, v92
	v_exp_f32_e32 v93, v93
	v_add_f32_e32 v92, 1.0, v92
	v_add_f32_e32 v93, 1.0, v93
	v_rcp_f32_e32 v92, v92
	v_rcp_f32_e32 v93, v93
	s_nop 0
	v_pk_mul_f32 v[82:83], v[82:83], v[92:93]
	s_nop 0
	v_pk_mul_f32 v[92:93], v[84:85], v[82:83]
	v_cvt_pk_bf16_f32 v82, v86, v87
	v_cvt_pk_bf16_f32 v83, v88, v89
	v_cvt_pk_bf16_f32 v84, v90, v91
	v_cvt_pk_bf16_f32 v85, v92, v93
	v_mad_i64_i32 v[86:87], s[6:7], v98, s4, v[142:143]
	global_store_dwordx4 v[86:87], v[82:85], off
	s_nop 1
	v_or_b32_e32 v82, 48, v144
	v_mov_b32_e32 v84, v161
	v_pk_mul_f32 v[78:79], v[78:79], v[84:85] op_sel_hi:[1,0]
	v_pk_mul_f32 v[70:71], v[70:71], v[84:85] op_sel_hi:[1,0]
	v_mul_f32_e32 v83, 0xbfb8aa3b, v78
	v_exp_f32_e32 v83, v83
	v_pk_mul_f32 v[72:73], v[72:73], v[84:85] op_sel_hi:[1,0]
	v_pk_mul_f32 v[74:75], v[74:75], v[84:85] op_sel_hi:[1,0]
	v_pk_mul_f32 v[66:67], v[66:67], v[84:85] op_sel_hi:[1,0]
	v_add_f32_e32 v83, 1.0, v83
	v_rcp_f32_e32 v86, v83
	v_mul_f32_e32 v83, 0xbfb8aa3b, v79
	v_exp_f32_e32 v83, v83
	v_pk_mul_f32 v[68:69], v[68:69], v[84:85] op_sel_hi:[1,0]
	v_add_f32_e32 v83, 1.0, v83
	v_rcp_f32_e32 v87, v83
	s_nop 0
	v_pk_mul_f32 v[78:79], v[78:79], v[86:87]
	s_nop 0
	v_pk_mul_f32 v[70:71], v[70:71], v[78:79]
	v_pk_mul_f32 v[78:79], v[80:81], v[84:85] op_sel_hi:[1,0]
	s_nop 0
	v_mul_f32_e32 v80, 0xbfb8aa3b, v78
	v_mul_f32_e32 v81, 0xbfb8aa3b, v79
	v_exp_f32_e32 v80, v80
	v_exp_f32_e32 v81, v81
	v_add_f32_e32 v80, 1.0, v80
	v_add_f32_e32 v81, 1.0, v81
	v_rcp_f32_e32 v80, v80
	v_rcp_f32_e32 v81, v81
	s_nop 0
	v_pk_mul_f32 v[78:79], v[78:79], v[80:81]
	s_nop 0
	v_pk_mul_f32 v[72:73], v[72:73], v[78:79]
	v_mul_f32_e32 v78, 0xbfb8aa3b, v74
	v_mul_f32_e32 v79, 0xbfb8aa3b, v75
	v_exp_f32_e32 v78, v78
	v_exp_f32_e32 v79, v79
	v_add_f32_e32 v78, 1.0, v78
	v_add_f32_e32 v79, 1.0, v79
	v_rcp_f32_e32 v78, v78
	v_rcp_f32_e32 v79, v79
	s_nop 0
	v_pk_mul_f32 v[74:75], v[74:75], v[78:79]
	s_nop 0
	v_pk_mul_f32 v[74:75], v[66:67], v[74:75]
	v_pk_mul_f32 v[66:67], v[76:77], v[84:85] op_sel_hi:[1,0]
	s_nop 0
	v_mul_f32_e32 v76, 0xbfb8aa3b, v66
	v_mul_f32_e32 v77, 0xbfb8aa3b, v67
	v_exp_f32_e32 v76, v76
	v_exp_f32_e32 v77, v77
	v_add_f32_e32 v76, 1.0, v76
	v_add_f32_e32 v77, 1.0, v77
	v_rcp_f32_e32 v76, v76
	v_rcp_f32_e32 v77, v77
	s_nop 0
	v_pk_mul_f32 v[66:67], v[66:67], v[76:77]
	s_nop 0
	v_pk_mul_f32 v[76:77], v[68:69], v[66:67]
	v_cvt_pk_bf16_f32 v66, v70, v71
	v_cvt_pk_bf16_f32 v67, v72, v73
	v_cvt_pk_bf16_f32 v68, v74, v75
	v_cvt_pk_bf16_f32 v69, v76, v77
	v_mad_i64_i32 v[70:71], s[6:7], v82, s4, v[142:143]
	global_store_dwordx4 v[70:71], v[66:69], off
	s_nop 1
	v_add_u32_e32 v66, 0x80, v144
	v_mov_b32_e32 v68, v162
	v_pk_mul_f32 v[62:63], v[62:63], v[68:69] op_sel_hi:[1,0]
	v_pk_mul_f32 v[54:55], v[54:55], v[68:69] op_sel_hi:[1,0]
	v_mul_f32_e32 v67, 0xbfb8aa3b, v62
	v_exp_f32_e32 v67, v67
	v_pk_mul_f32 v[56:57], v[56:57], v[68:69] op_sel_hi:[1,0]
	v_pk_mul_f32 v[58:59], v[58:59], v[68:69] op_sel_hi:[1,0]
	v_pk_mul_f32 v[50:51], v[50:51], v[68:69] op_sel_hi:[1,0]
	v_add_f32_e32 v67, 1.0, v67
	v_rcp_f32_e32 v70, v67
	v_mul_f32_e32 v67, 0xbfb8aa3b, v63
	v_exp_f32_e32 v67, v67
	v_pk_mul_f32 v[52:53], v[52:53], v[68:69] op_sel_hi:[1,0]
	v_add_f32_e32 v67, 1.0, v67
	v_rcp_f32_e32 v71, v67
	s_nop 0
	v_pk_mul_f32 v[62:63], v[62:63], v[70:71]
	s_nop 0
	v_pk_mul_f32 v[54:55], v[54:55], v[62:63]
	v_pk_mul_f32 v[62:63], v[64:65], v[68:69] op_sel_hi:[1,0]
	s_nop 0
	v_mul_f32_e32 v64, 0xbfb8aa3b, v62
	v_mul_f32_e32 v65, 0xbfb8aa3b, v63
	v_exp_f32_e32 v64, v64
	v_exp_f32_e32 v65, v65
	v_add_f32_e32 v64, 1.0, v64
	v_add_f32_e32 v65, 1.0, v65
	v_rcp_f32_e32 v64, v64
	v_rcp_f32_e32 v65, v65
	s_nop 0
	v_pk_mul_f32 v[62:63], v[62:63], v[64:65]
	s_nop 0
	v_pk_mul_f32 v[56:57], v[56:57], v[62:63]
	v_mul_f32_e32 v62, 0xbfb8aa3b, v58
	v_mul_f32_e32 v63, 0xbfb8aa3b, v59
	v_exp_f32_e32 v62, v62
	v_exp_f32_e32 v63, v63
	v_add_f32_e32 v62, 1.0, v62
	v_add_f32_e32 v63, 1.0, v63
	v_rcp_f32_e32 v62, v62
	v_rcp_f32_e32 v63, v63
	s_nop 0
	v_pk_mul_f32 v[58:59], v[58:59], v[62:63]
	s_nop 0
	v_pk_mul_f32 v[58:59], v[50:51], v[58:59]
	v_pk_mul_f32 v[50:51], v[60:61], v[68:69] op_sel_hi:[1,0]
	s_nop 0
	v_mul_f32_e32 v60, 0xbfb8aa3b, v50
	v_mul_f32_e32 v61, 0xbfb8aa3b, v51
	v_exp_f32_e32 v60, v60
	v_exp_f32_e32 v61, v61
	v_add_f32_e32 v60, 1.0, v60
	v_add_f32_e32 v61, 1.0, v61
	v_rcp_f32_e32 v60, v60
	v_rcp_f32_e32 v61, v61
	s_nop 0
	v_pk_mul_f32 v[50:51], v[50:51], v[60:61]
	s_nop 0
	v_pk_mul_f32 v[60:61], v[52:53], v[50:51]
	v_cvt_pk_bf16_f32 v50, v54, v55
	v_cvt_pk_bf16_f32 v51, v56, v57
	v_cvt_pk_bf16_f32 v52, v58, v59
	v_cvt_pk_bf16_f32 v53, v60, v61
	v_mad_i64_i32 v[54:55], s[6:7], v66, s4, v[142:143]
	global_store_dwordx4 v[54:55], v[50:53], off
	s_nop 1
	v_add_u32_e32 v50, 0x90, v144
	v_mov_b32_e32 v52, v163
	v_pk_mul_f32 v[46:47], v[46:47], v[52:53] op_sel_hi:[1,0]
	v_pk_mul_f32 v[38:39], v[38:39], v[52:53] op_sel_hi:[1,0]
	v_mul_f32_e32 v51, 0xbfb8aa3b, v46
	v_exp_f32_e32 v51, v51
	v_pk_mul_f32 v[40:41], v[40:41], v[52:53] op_sel_hi:[1,0]
; __device__ __forceinline__ unsigned pk2(float lo, float hi) { f32x2_t v = {lo, hi}; bf16x2_t b = __builtin_convertvector(v, bf16x2_t); return __builtin_bit_cast(unsigned, b); }
; __device__ __forceinline__ float fast_sigmoid(float x) { return __builtin_amdgcn_rcpf(1.f + __expf(-x)); }
; #define PG8_BAR __builtin_amdgcn_s_barrier()
; template <class Epi>
; __device__ __forceinline__ void gemm_phase(LAS unsigned char* lds, int wave_s, const Gemm g, const StaticOrder S, const Epi E) {
;     ...
;         if (wr == 0) PG8_BAR;
;         E(acc, cur, wr, wc, fr, fq);
;         if (!has_next) break;
; #pragma unroll
;         for (int a = 0; a < 2; ++a)
; #pragma unroll
;             for (int b = 0; b < 2; ++b)
; #pragma unroll
;                 for (int m = 0; m < 4; ++m)
; #pragma unroll
;                     for (int n = 0; n < 2; ++n) acc[a][b][m][n] = (f32x4){0.f, 0.f, 0.f, 0.f};
;         cur = nxt; cA = nA; cB = nB; ++ui;
;         if (wr == 1) PG8_BAR;
;     __device__ __forceinline__ void operator()(const f32x4 (&acc)[2][2][4][2], const Unit& u, int wr, int wc, int fr, int fq) const {
;         const int row0 = u.pm * BM + wr * 64 + fr, col0 = u.pn * 128 + wc * 32 + 8 * fq;
; #pragma unroll
;         for (int ai = 0; ai < 2; ++ai)
; #pragma unroll
;             for (int m = 0; m < 4; ++m) {
;                 const int row = row0 + ai * HALF + m * 16;
;                 const float rs = rsqrtf(row_ssq(ssq, 16, 4, row, fq) * (1.f / 1024.f) + EPS);
;                 float r[8];
; #pragma unroll
;                 for (int n = 0; n < 2; ++n)
; #pragma unroll
;                     for (int e = 0; e < 4; ++e) { const float gv = acc[ai][0][m][n][e] * rs, uv = acc[ai][1][m][n][e] * rs; r[n * 4 + e] = gv * fast_sigmoid(gv) * uv; }
;                 u32x4 w; w.x = pk2(r[0], r[1]); w.y = pk2(r[2], r[3]); w.z = pk2(r[4], r[5]); w.w = pk2(r[6], r[7]);
;                 *(u32x4*)(O + (size_t)row * DFF + col0) = w;
	v_pk_mul_f32 v[42:43], v[42:43], v[52:53] op_sel_hi:[1,0]
	v_pk_mul_f32 v[34:35], v[34:35], v[52:53] op_sel_hi:[1,0]
	v_add_f32_e32 v51, 1.0, v51
	v_rcp_f32_e32 v54, v51
	v_mul_f32_e32 v51, 0xbfb8aa3b, v47
	v_exp_f32_e32 v51, v51
	v_pk_mul_f32 v[36:37], v[36:37], v[52:53] op_sel_hi:[1,0]
	v_add_f32_e32 v51, 1.0, v51
	v_rcp_f32_e32 v55, v51
	s_nop 0
	v_pk_mul_f32 v[46:47], v[46:47], v[54:55]
	s_nop 0
	v_pk_mul_f32 v[38:39], v[38:39], v[46:47]
	v_pk_mul_f32 v[46:47], v[48:49], v[52:53] op_sel_hi:[1,0]
	s_nop 0
	v_mul_f32_e32 v48, 0xbfb8aa3b, v46
	v_mul_f32_e32 v49, 0xbfb8aa3b, v47
	v_exp_f32_e32 v48, v48
	v_exp_f32_e32 v49, v49
	v_add_f32_e32 v48, 1.0, v48
	v_add_f32_e32 v49, 1.0, v49
	v_rcp_f32_e32 v48, v48
	v_rcp_f32_e32 v49, v49
	s_nop 0
	v_pk_mul_f32 v[46:47], v[46:47], v[48:49]
	s_nop 0
	v_pk_mul_f32 v[40:41], v[40:41], v[46:47]
	v_mul_f32_e32 v46, 0xbfb8aa3b, v42
	v_mul_f32_e32 v47, 0xbfb8aa3b, v43
	v_exp_f32_e32 v46, v46
	v_exp_f32_e32 v47, v47
	v_add_f32_e32 v46, 1.0, v46
	v_add_f32_e32 v47, 1.0, v47
	v_rcp_f32_e32 v46, v46
	v_rcp_f32_e32 v47, v47
	s_nop 0
	v_pk_mul_f32 v[42:43], v[42:43], v[46:47]
	s_nop 0
	v_pk_mul_f32 v[42:43], v[34:35], v[42:43]
	v_pk_mul_f32 v[34:35], v[44:45], v[52:53] op_sel_hi:[1,0]
	s_nop 0
	v_mul_f32_e32 v44, 0xbfb8aa3b, v34
	v_mul_f32_e32 v45, 0xbfb8aa3b, v35
	v_exp_f32_e32 v44, v44
	v_exp_f32_e32 v45, v45
	v_add_f32_e32 v44, 1.0, v44
	v_add_f32_e32 v45, 1.0, v45
	v_rcp_f32_e32 v44, v44
	v_rcp_f32_e32 v45, v45
	s_nop 0
	v_pk_mul_f32 v[34:35], v[34:35], v[44:45]
	s_nop 0
	v_pk_mul_f32 v[44:45], v[36:37], v[34:35]
	v_cvt_pk_bf16_f32 v34, v38, v39
	v_cvt_pk_bf16_f32 v35, v40, v41
	v_cvt_pk_bf16_f32 v36, v42, v43
	v_cvt_pk_bf16_f32 v37, v44, v45
	v_mad_i64_i32 v[38:39], s[6:7], v50, s4, v[142:143]
	global_store_dwordx4 v[38:39], v[34:37], off
	s_nop 1
	v_add_u32_e32 v34, 0xa0, v144
	v_mov_b32_e32 v36, v164
	v_pk_mul_f32 v[30:31], v[30:31], v[36:37] op_sel_hi:[1,0]
	v_pk_mul_f32 v[22:23], v[22:23], v[36:37] op_sel_hi:[1,0]
	v_mul_f32_e32 v35, 0xbfb8aa3b, v30
	v_exp_f32_e32 v35, v35
	v_pk_mul_f32 v[24:25], v[24:25], v[36:37] op_sel_hi:[1,0]
	v_pk_mul_f32 v[26:27], v[26:27], v[36:37] op_sel_hi:[1,0]
	v_pk_mul_f32 v[18:19], v[18:19], v[36:37] op_sel_hi:[1,0]
	v_add_f32_e32 v35, 1.0, v35
	v_rcp_f32_e32 v38, v35
	v_mul_f32_e32 v35, 0xbfb8aa3b, v31
	v_exp_f32_e32 v35, v35
	v_pk_mul_f32 v[20:21], v[20:21], v[36:37] op_sel_hi:[1,0]
	v_add_f32_e32 v35, 1.0, v35
	v_rcp_f32_e32 v39, v35
	s_nop 0
	v_pk_mul_f32 v[30:31], v[30:31], v[38:39]
	s_nop 0
	v_pk_mul_f32 v[22:23], v[22:23], v[30:31]
	v_pk_mul_f32 v[30:31], v[32:33], v[36:37] op_sel_hi:[1,0]
	s_nop 0
	v_mul_f32_e32 v32, 0xbfb8aa3b, v30
	v_mul_f32_e32 v33, 0xbfb8aa3b, v31
	v_exp_f32_e32 v32, v32
	v_exp_f32_e32 v33, v33
	v_add_f32_e32 v32, 1.0, v32
	v_add_f32_e32 v33, 1.0, v33
	v_rcp_f32_e32 v32, v32
	v_rcp_f32_e32 v33, v33
	s_nop 0
	v_pk_mul_f32 v[30:31], v[30:31], v[32:33]
	s_nop 0
	v_pk_mul_f32 v[24:25], v[24:25], v[30:31]
	v_mul_f32_e32 v30, 0xbfb8aa3b, v26
	v_mul_f32_e32 v31, 0xbfb8aa3b, v27
	v_exp_f32_e32 v30, v30
	v_exp_f32_e32 v31, v31
	v_add_f32_e32 v30, 1.0, v30
	v_add_f32_e32 v31, 1.0, v31
	v_rcp_f32_e32 v30, v30
	v_rcp_f32_e32 v31, v31
	s_nop 0
	v_pk_mul_f32 v[26:27], v[26:27], v[30:31]
	s_nop 0
	v_pk_mul_f32 v[26:27], v[18:19], v[26:27]
	v_pk_mul_f32 v[18:19], v[28:29], v[36:37] op_sel_hi:[1,0]
	s_nop 0
	v_mul_f32_e32 v28, 0xbfb8aa3b, v18
	v_mul_f32_e32 v29, 0xbfb8aa3b, v19
	v_exp_f32_e32 v28, v28
	v_exp_f32_e32 v29, v29
	v_add_f32_e32 v28, 1.0, v28
	v_add_f32_e32 v29, 1.0, v29
	v_rcp_f32_e32 v28, v28
	v_rcp_f32_e32 v29, v29
	s_nop 0
	v_pk_mul_f32 v[18:19], v[18:19], v[28:29]
	s_nop 0
	v_pk_mul_f32 v[28:29], v[20:21], v[18:19]
	v_cvt_pk_bf16_f32 v18, v22, v23
	v_cvt_pk_bf16_f32 v19, v24, v25
	v_cvt_pk_bf16_f32 v20, v26, v27
	v_cvt_pk_bf16_f32 v21, v28, v29
	v_mad_i64_i32 v[22:23], s[6:7], v34, s4, v[142:143]
	global_store_dwordx4 v[22:23], v[18:21], off
	s_nop 1
	v_add_u32_e32 v18, 0xb0, v144
	v_mov_b32_e32 v20, v165
	v_pk_mul_f32 v[14:15], v[14:15], v[20:21] op_sel_hi:[1,0]
	v_pk_mul_f32 v[6:7], v[6:7], v[20:21] op_sel_hi:[1,0]
	v_mul_f32_e32 v19, 0xbfb8aa3b, v14
	v_exp_f32_e32 v19, v19
	v_pk_mul_f32 v[8:9], v[8:9], v[20:21] op_sel_hi:[1,0]
	v_pk_mul_f32 v[10:11], v[10:11], v[20:21] op_sel_hi:[1,0]
	v_pk_mul_f32 v[2:3], v[2:3], v[20:21] op_sel_hi:[1,0]
	v_add_f32_e32 v19, 1.0, v19
	v_rcp_f32_e32 v22, v19
	v_mul_f32_e32 v19, 0xbfb8aa3b, v15
	v_exp_f32_e32 v19, v19
	v_pk_mul_f32 v[4:5], v[4:5], v[20:21] op_sel_hi:[1,0]
	s_andn2_b64 vcc, exec, s[42:43]
	v_add_f32_e32 v19, 1.0, v19
	v_rcp_f32_e32 v23, v19
	s_nop 0
	v_pk_mul_f32 v[14:15], v[14:15], v[22:23]
	s_nop 0
	v_pk_mul_f32 v[6:7], v[6:7], v[14:15]
	v_pk_mul_f32 v[14:15], v[16:17], v[20:21] op_sel_hi:[1,0]
	s_nop 0
	v_mul_f32_e32 v16, 0xbfb8aa3b, v14
	v_mul_f32_e32 v17, 0xbfb8aa3b, v15
	v_exp_f32_e32 v16, v16
	v_exp_f32_e32 v17, v17
	v_add_f32_e32 v16, 1.0, v16
	v_add_f32_e32 v17, 1.0, v17
	v_rcp_f32_e32 v16, v16
	v_rcp_f32_e32 v17, v17
	s_nop 0
	v_pk_mul_f32 v[14:15], v[14:15], v[16:17]
	s_nop 0
	v_pk_mul_f32 v[8:9], v[8:9], v[14:15]
	v_mul_f32_e32 v14, 0xbfb8aa3b, v10
	v_mul_f32_e32 v15, 0xbfb8aa3b, v11
	v_exp_f32_e32 v14, v14
	v_exp_f32_e32 v15, v15
	v_add_f32_e32 v14, 1.0, v14
	v_add_f32_e32 v15, 1.0, v15
	v_rcp_f32_e32 v14, v14
	v_rcp_f32_e32 v15, v15
	s_nop 0
	v_pk_mul_f32 v[10:11], v[10:11], v[14:15]
	s_nop 0
	v_pk_mul_f32 v[10:11], v[2:3], v[10:11]
	v_pk_mul_f32 v[2:3], v[12:13], v[20:21] op_sel_hi:[1,0]
	s_nop 0
	v_mul_f32_e32 v12, 0xbfb8aa3b, v2
	v_mul_f32_e32 v13, 0xbfb8aa3b, v3
	v_exp_f32_e32 v12, v12
	v_exp_f32_e32 v13, v13
	v_add_f32_e32 v12, 1.0, v12
	v_add_f32_e32 v13, 1.0, v13
	v_rcp_f32_e32 v12, v12
	v_rcp_f32_e32 v13, v13
	s_nop 0
	v_pk_mul_f32 v[2:3], v[2:3], v[12:13]
	s_nop 0
	v_pk_mul_f32 v[12:13], v[4:5], v[2:3]
	v_cvt_pk_bf16_f32 v2, v6, v7
	v_cvt_pk_bf16_f32 v3, v8, v9
	v_cvt_pk_bf16_f32 v4, v10, v11
	v_cvt_pk_bf16_f32 v5, v12, v13
	v_mad_i64_i32 v[6:7], s[6:7], v18, s4, v[142:143]
	global_store_dwordx4 v[6:7], v[2:5], off
	s_cbranch_vccnz .LBB0_1147
	s_andn2_b64 vcc, exec, s[0:1]
	s_cbranch_vccnz .LBB0_1146
	s_barrier
	s_branch .LBB0_1146
